# scan: each wave's 10 DMA pieces split 5/5; the W/Qd pieces of chunk n+2 are issued right after the mid-step barrier of step n so every piece gets 1.5 steps of flight time
# speedup vs baseline: 1.0140x; 1.0029x over previous
.LBB0_711:
	s_and_b32 s57, s51, 1
	s_cmp_eq_u32 s88, 0xfe0000
	s_cbranch_scc1 .Lscan_last
	s_and_b64 vcc, exec, s[22:23]
	s_cbranch_vccz .LBB0_721
	s_xor_b32 s60, s57, 1
	v_mad_i64_i32 v[36:37], s[46:47], s55, v245, v[32:33]
	s_mul_i32 s60, s60, 0xf000
	s_add_i32 s61, s60, s49
	s_addk_i32 s61, 0xf800
	v_lshl_add_u64 v[36:37], v[36:37], 0, v[220:221]
	s_mov_b32 s10, 0x7800
	s_mov_b32 s11, 0
	s_cmp_lg_u32 s51, 0
	s_cbranch_scc1 .Lsd_b
	v_mov_b64_e32 v[224:225], v[36:37]
	s_mov_b32 m0, s61
	s_nop 0
	global_load_lds_dwordx4 v[224:225], off
	s_addk_i32 s61, 0x1800
	s_mov_b32 m0, s61
	v_lshl_add_u64 v[224:225], v[224:225], 0, v[218:219]
	global_load_lds_dwordx4 v[224:225], off
	s_addk_i32 s61, 0x1800
	s_mov_b32 m0, s61
	v_lshl_add_u64 v[224:225], v[224:225], 0, v[218:219]
	global_load_lds_dwordx4 v[224:225], off
	s_addk_i32 s61, 0x1800
	s_mov_b32 m0, s61
	v_lshl_add_u64 v[224:225], v[224:225], 0, v[218:219]
	global_load_lds_dwordx4 v[224:225], off
	s_addk_i32 s61, 0x1800
	s_mov_b32 m0, s61
	v_lshl_add_u64 v[224:225], v[224:225], 0, v[218:219]
	global_load_lds_dwordx4 v[224:225], off
	s_addk_i32 s61, 0xa000
.Lsd_b:
	s_addk_i32 s61, 0x7800
	v_lshl_add_u64 v[36:37], v[36:37], 0, s[10:11]
	s_mov_b32 m0, s61
	s_nop 0
	global_load_lds_dwordx4 v[36:37], off
	s_addk_i32 s61, 0x1800
	s_mov_b32 m0, s61
	v_lshl_add_u64 v[36:37], v[36:37], 0, v[218:219]
	global_load_lds_dwordx4 v[36:37], off
	s_addk_i32 s61, 0x1800
	s_mov_b32 m0, s61
	v_lshl_add_u64 v[36:37], v[36:37], 0, v[218:219]
	global_load_lds_dwordx4 v[36:37], off
	s_addk_i32 s61, 0x1800
	s_mov_b32 m0, s61
	v_lshl_add_u64 v[36:37], v[36:37], 0, v[218:219]
	global_load_lds_dwordx4 v[36:37], off
	s_addk_i32 s61, 0x1800
	s_mov_b32 m0, s61
	v_lshl_add_u64 v[36:37], v[36:37], 0, v[218:219]
	v_lshl_add_u64 v[36:37], v[36:37], 0, v[222:223]
	global_load_lds_dwordx4 v[36:37], off
	s_waitcnt vmcnt(10)
	s_barrier
	s_cmp_eq_u32 s88, 0xfc0000
	s_cbranch_scc1 .Lsd_l2
	s_add_i32 s60, s55, 4
	s_nop 0
	v_mad_i64_i32 v[36:37], s[46:47], s60, v245, v[32:33]
	s_mul_i32 s60, s57, 0xf000
	s_add_i32 s61, s60, s49
	s_addk_i32 s61, 0xf800
	v_lshl_add_u64 v[36:37], v[36:37], 0, v[220:221]
	s_mov_b32 m0, s61
	s_nop 0
	global_load_lds_dwordx4 v[36:37], off
	s_addk_i32 s61, 0x1800
	s_mov_b32 m0, s61
	v_lshl_add_u64 v[36:37], v[36:37], 0, v[218:219]
	global_load_lds_dwordx4 v[36:37], off
	s_addk_i32 s61, 0x1800
	s_mov_b32 m0, s61
	v_lshl_add_u64 v[36:37], v[36:37], 0, v[218:219]
	global_load_lds_dwordx4 v[36:37], off
	s_addk_i32 s61, 0x1800
	s_mov_b32 m0, s61
	v_lshl_add_u64 v[36:37], v[36:37], 0, v[218:219]
	global_load_lds_dwordx4 v[36:37], off
	s_addk_i32 s61, 0x1800
	s_mov_b32 m0, s61
	v_lshl_add_u64 v[36:37], v[36:37], 0, v[218:219]
	global_load_lds_dwordx4 v[36:37], off
	s_waitcnt vmcnt(10)
	s_branch .LBB0_710
.Lsd_l2:
	s_waitcnt vmcnt(0)
	s_branch .LBB0_710

.LBB0_723:
	s_andn2_b64 vcc, exec, s[46:47]
	s_cbranch_vccnz .LBB0_710
	s_mul_i32 s57, s57, 0xf000
	s_add_i32 s46, s57, 0
	v_mov_b32_e32 v36, s56
	v_add_u32_e32 v37, s46, v192
	ds_read_b32 v36, v36
	ds_read_b128 v[40:43], v37
	ds_read_b128 v[44:47], v37 offset:1024
	ds_read_b128 v[48:51], v37 offset:16384
	ds_read_b128 v[52:55], v37 offset:17408
	ds_read_b128 v[56:59], v37 offset:4096
	ds_read_b128 v[60:63], v37 offset:5120
	ds_read_b128 v[64:67], v37 offset:20480
	ds_read_b128 v[68:71], v37 offset:21504
	ds_read_b128 v[72:75], v37 offset:8192
	ds_read_b128 v[76:79], v37 offset:9216
	ds_read_b128 v[80:83], v37 offset:24576
	ds_read_b128 v[84:87], v37 offset:25600
	ds_read_b128 v[88:91], v37 offset:12288
	ds_read_b128 v[92:95], v37 offset:13312
	ds_read_b128 v[96:99], v37 offset:28672
	ds_read_b128 v[100:103], v37 offset:29696
	ds_read_b128 v[104:107], v37 offset:2048
	ds_read_b128 v[108:111], v37 offset:3072
	ds_read_b128 v[112:115], v37 offset:18432
	ds_read_b128 v[116:119], v37 offset:19456
	ds_read_b128 v[120:123], v37 offset:6144
	ds_read_b128 v[124:127], v37 offset:7168
	ds_read_b128 v[128:131], v37 offset:22528
	ds_read_b128 v[132:135], v37 offset:23552
	ds_read_b128 v[136:139], v37 offset:10240
	ds_read_b128 v[140:143], v37 offset:11264
	ds_read_b128 v[144:147], v37 offset:26624
	ds_read_b128 v[148:151], v37 offset:27648
	ds_read_b128 v[152:155], v37 offset:14336
	ds_read_b128 v[156:159], v37 offset:15360
	v_cvt_pk_bf16_f32 v168, v20, v21
	v_cvt_pk_bf16_f32 v169, v22, v23
	v_cvt_pk_bf16_f32 v170, v28, v29
	v_cvt_pk_bf16_f32 v171, v30, v31
	v_cvt_pk_bf16_f32 v172, v24, v25
	v_cvt_pk_bf16_f32 v173, v26, v27
	v_cvt_pk_bf16_f32 v174, v16, v17
	v_cvt_pk_bf16_f32 v175, v18, v19
	v_cvt_pk_bf16_f32 v176, v12, v13
	v_cvt_pk_bf16_f32 v177, v14, v15
	v_cvt_pk_bf16_f32 v178, v8, v9
	v_cvt_pk_bf16_f32 v179, v10, v11
	v_cvt_pk_bf16_f32 v180, v4, v5
	v_cvt_pk_bf16_f32 v181, v6, v7
	v_cvt_pk_bf16_f32 v182, v0, v1
	v_cvt_pk_bf16_f32 v183, v2, v3
	s_waitcnt lgkmcnt(0)
	v_mfma_f32_16x16x32_bf16 v[40:43], v[40:43], v[168:171], 0
	v_mfma_f32_16x16x32_bf16 v[56:59], v[56:59], v[168:171], 0
	v_mfma_f32_16x16x32_bf16 v[72:75], v[72:75], v[168:171], 0
	v_mfma_f32_16x16x32_bf16 v[88:91], v[88:91], v[168:171], 0
	v_mfma_f32_16x16x32_bf16 v[48:51], v[168:171], v[48:51], 0
	v_mfma_f32_16x16x32_bf16 v[64:67], v[168:171], v[64:67], 0
	v_mfma_f32_16x16x32_bf16 v[80:83], v[168:171], v[80:83], 0
	v_mfma_f32_16x16x32_bf16 v[96:99], v[168:171], v[96:99], 0
	v_mfma_f32_16x16x32_bf16 v[40:43], v[44:47], v[172:175], v[40:43]
	v_mfma_f32_16x16x32_bf16 v[44:47], v[60:63], v[172:175], v[56:59]
	v_mfma_f32_16x16x32_bf16 v[56:59], v[76:79], v[172:175], v[72:75]
	v_mfma_f32_16x16x32_bf16 v[60:63], v[92:95], v[172:175], v[88:91]
	v_mfma_f32_16x16x32_bf16 v[48:51], v[172:175], v[52:55], v[48:51]
	v_mfma_f32_16x16x32_bf16 v[52:55], v[172:175], v[68:71], v[64:67]
	v_mfma_f32_16x16x32_bf16 v[64:67], v[172:175], v[84:87], v[80:83]
	v_mfma_f32_16x16x32_bf16 v[68:71], v[172:175], v[100:103], v[96:99]
	s_barrier
	ds_read_b128 v[160:163], v37 offset:30720
	ds_read_b128 v[164:167], v37 offset:31744
	ds_read_b128 v[72:75], v37 offset:32768
	ds_read_b128 v[76:79], v37 offset:34816
	ds_read_b128 v[80:83], v37 offset:36864
	ds_read_b128 v[84:87], v37 offset:38912
	ds_read_b128 v[88:91], v37 offset:40960
	ds_read_b128 v[92:95], v37 offset:43008
	ds_read_b128 v[96:99], v37 offset:45056
	ds_read_b128 v[100:103], v37 offset:47104
	ds_read_b128 v[168:171], v37 offset:49152
	ds_read_b128 v[172:175], v37 offset:51200
	ds_read_b128 v[184:187], v37 offset:53248
	ds_read_b128 v[188:191], v37 offset:54272
	ds_read_b128 v[202:205], v37 offset:55296
	ds_read_b128 v[206:209], v37 offset:56320
	s_add_i32 s46, s46, s54
	v_add_u32_e32 v39, s46, v38
	ds_read_b128 v[210:213], v39 offset:57344
	ds_read_b128 v[214:217], v39 offset:57360
	s_waitcnt lgkmcnt(15)
	v_mfma_f32_16x16x32_bf16 v[40:43], v[104:107], v[176:179], v[40:43]
	v_mfma_f32_16x16x32_bf16 v[44:47], v[120:123], v[176:179], v[44:47]
	v_mfma_f32_16x16x32_bf16 v[56:59], v[136:139], v[176:179], v[56:59]
	v_mfma_f32_16x16x32_bf16 v[60:63], v[152:155], v[176:179], v[60:63]
	v_mfma_f32_16x16x32_bf16 v[48:51], v[176:179], v[112:115], v[48:51]
	v_mfma_f32_16x16x32_bf16 v[52:55], v[176:179], v[128:131], v[52:55]
	v_mfma_f32_16x16x32_bf16 v[64:67], v[176:179], v[144:147], v[64:67]
	v_mfma_f32_16x16x32_bf16 v[68:71], v[176:179], v[160:163], v[68:71]
	v_mfma_f32_16x16x32_bf16 v[40:43], v[108:111], v[180:183], v[40:43]
	v_mfma_f32_16x16x32_bf16 v[44:47], v[124:127], v[180:183], v[44:47]
	v_mfma_f32_16x16x32_bf16 v[56:59], v[140:143], v[180:183], v[56:59]
	v_mfma_f32_16x16x32_bf16 v[60:63], v[156:159], v[180:183], v[60:63]
	v_mfma_f32_16x16x32_bf16 v[48:51], v[180:183], v[116:119], v[48:51]
	v_mfma_f32_16x16x32_bf16 v[52:55], v[180:183], v[132:135], v[52:55]
	v_mfma_f32_16x16x32_bf16 v[64:67], v[180:183], v[148:151], v[64:67]
	v_mfma_f32_16x16x32_bf16 v[68:71], v[180:183], v[164:167], v[68:71]
	ds_read_b128 v[104:107], v37 offset:33792
	ds_read_b128 v[108:111], v37 offset:35840
	ds_read_b128 v[112:115], v37 offset:37888
	ds_read_b128 v[116:119], v37 offset:39936
	ds_read_b128 v[120:123], v37 offset:41984
	ds_read_b128 v[124:127], v37 offset:44032
	ds_read_b128 v[128:131], v37 offset:46080
	ds_read_b128 v[132:135], v37 offset:48128
	s_waitcnt lgkmcnt(0)
	v_lshlrev_b32_e32 v37, 16, v210
	v_and_b32_e32 v39, 0xffff0000, v210
	v_lshlrev_b32_e32 v136, 16, v211
	v_and_b32_e32 v137, 0xffff0000, v211
	v_sub_f32_e32 v43, v137, v43
	v_sub_f32_e32 v42, v136, v42
	v_sub_f32_e32 v39, v39, v41
	v_sub_f32_e32 v37, v37, v40
	v_lshlrev_b32_e32 v40, 16, v212
	v_and_b32_e32 v41, 0xffff0000, v212
	v_lshlrev_b32_e32 v136, 16, v213
	v_and_b32_e32 v137, 0xffff0000, v213
	v_sub_f32_e32 v47, v137, v47
	v_sub_f32_e32 v46, v136, v46
	v_sub_f32_e32 v45, v41, v45
	v_sub_f32_e32 v44, v40, v44
	v_lshlrev_b32_e32 v40, 16, v214
	v_and_b32_e32 v41, 0xffff0000, v214
	v_lshlrev_b32_e32 v136, 16, v215
	v_and_b32_e32 v137, 0xffff0000, v215
	v_sub_f32_e32 v59, v137, v59
	v_sub_f32_e32 v58, v136, v58
	v_sub_f32_e32 v57, v41, v57
	v_sub_f32_e32 v56, v40, v56
	v_lshlrev_b32_e32 v40, 16, v216
	v_and_b32_e32 v41, 0xffff0000, v216
	v_lshlrev_b32_e32 v136, 16, v217
	v_and_b32_e32 v137, 0xffff0000, v217
	v_sub_f32_e32 v63, v137, v63
	v_sub_f32_e32 v62, v136, v62
	v_sub_f32_e32 v61, v41, v61
	v_sub_f32_e32 v60, v40, v60
	v_pk_mul_f32 v[22:23], v[22:23], v[36:37] op_sel_hi:[1,0]
	v_pk_mul_f32 v[20:21], v[20:21], v[36:37] op_sel_hi:[1,0]
	v_pk_mul_f32 v[30:31], v[30:31], v[36:37] op_sel_hi:[1,0]
	v_pk_mul_f32 v[28:29], v[28:29], v[36:37] op_sel_hi:[1,0]
	v_pk_mul_f32 v[26:27], v[26:27], v[36:37] op_sel_hi:[1,0]
	v_pk_mul_f32 v[24:25], v[24:25], v[36:37] op_sel_hi:[1,0]
	v_pk_mul_f32 v[18:19], v[18:19], v[36:37] op_sel_hi:[1,0]
	v_pk_mul_f32 v[16:17], v[16:17], v[36:37] op_sel_hi:[1,0]
	v_pk_mul_f32 v[14:15], v[14:15], v[36:37] op_sel_hi:[1,0]
	v_pk_mul_f32 v[12:13], v[12:13], v[36:37] op_sel_hi:[1,0]
	v_pk_mul_f32 v[10:11], v[10:11], v[36:37] op_sel_hi:[1,0]
	v_pk_mul_f32 v[8:9], v[8:9], v[36:37] op_sel_hi:[1,0]
	v_pk_mul_f32 v[6:7], v[6:7], v[36:37] op_sel_hi:[1,0]
	v_pk_mul_f32 v[4:5], v[4:5], v[36:37] op_sel_hi:[1,0]
	v_pk_mul_f32 v[2:3], v[2:3], v[36:37] op_sel_hi:[1,0]
	v_pk_mul_f32 v[0:1], v[0:1], v[36:37] op_sel_hi:[1,0]
	v_cvt_pk_bf16_f32 v40, v37, v39
	v_cvt_pk_bf16_f32 v41, v42, v43
	v_cvt_pk_bf16_f32 v42, v44, v45
	v_cvt_pk_bf16_f32 v43, v46, v47
	v_cvt_pk_bf16_f32 v44, v56, v57
	v_cvt_pk_bf16_f32 v45, v58, v59
	v_cvt_pk_bf16_f32 v46, v60, v61
	v_cvt_pk_bf16_f32 v47, v62, v63
	v_mfma_f32_16x16x32_bf16 v[20:23], v[72:75], v[40:43], v[20:23]
	v_mfma_f32_16x16x32_bf16 v[28:31], v[76:79], v[40:43], v[28:31]
	v_mfma_f32_16x16x32_bf16 v[24:27], v[80:83], v[40:43], v[24:27]
	v_mfma_f32_16x16x32_bf16 v[16:19], v[84:87], v[40:43], v[16:19]
	v_mfma_f32_16x16x32_bf16 v[12:15], v[88:91], v[40:43], v[12:15]
	v_mfma_f32_16x16x32_bf16 v[8:11], v[92:95], v[40:43], v[8:11]
	v_mfma_f32_16x16x32_bf16 v[4:7], v[96:99], v[40:43], v[4:7]
	v_mfma_f32_16x16x32_bf16 v[0:3], v[100:103], v[40:43], v[0:3]
	v_mfma_f32_16x16x32_bf16 v[48:51], v[40:43], v[168:171], v[48:51]
	v_mfma_f32_16x16x32_bf16 v[52:55], v[40:43], v[172:175], v[52:55]
	v_mfma_f32_16x16x32_bf16 v[56:59], v[40:43], v[184:187], v[64:67]
	v_mfma_f32_16x16x32_bf16 v[40:43], v[40:43], v[202:205], v[68:71]
	v_mfma_f32_16x16x32_bf16 v[20:23], v[104:107], v[44:47], v[20:23]
	v_mfma_f32_16x16x32_bf16 v[28:31], v[108:111], v[44:47], v[28:31]
	v_mfma_f32_16x16x32_bf16 v[24:27], v[112:115], v[44:47], v[24:27]
	v_mfma_f32_16x16x32_bf16 v[16:19], v[116:119], v[44:47], v[16:19]
	v_mfma_f32_16x16x32_bf16 v[12:15], v[120:123], v[44:47], v[12:15]
	v_mfma_f32_16x16x32_bf16 v[8:11], v[124:127], v[44:47], v[8:11]
	v_mfma_f32_16x16x32_bf16 v[4:7], v[128:131], v[44:47], v[4:7]
	v_mfma_f32_16x16x32_bf16 v[0:3], v[132:135], v[44:47], v[0:3]
	v_mfma_f32_16x16x32_bf16 v[56:59], v[44:47], v[188:191], v[56:59]
	v_mfma_f32_16x16x32_bf16 v[40:43], v[44:47], v[206:209], v[40:43]
	v_lshl_add_u64 v[36:37], v[34:35], 0, s[88:89]
	s_mov_b32 s46, 0xec00000
	v_add_co_u32_e32 v46, vcc, s46, v36
	v_cvt_pk_bf16_f32 v44, v48, v49
	v_cvt_pk_bf16_f32 v45, v50, v51
	v_addc_co_u32_e32 v47, vcc, 0, v37, vcc
	s_mov_b32 s46, 0xec08000
	global_store_dwordx2 v[46:47], v[44:45], off
	v_add_co_u32_e32 v46, vcc, s46, v36
	v_cvt_pk_bf16_f32 v44, v52, v53
	v_cvt_pk_bf16_f32 v45, v54, v55
	v_addc_co_u32_e32 v47, vcc, 0, v37, vcc
	s_mov_b32 s46, 0xec10000
	global_store_dwordx2 v[46:47], v[44:45], off
	v_add_co_u32_e32 v46, vcc, s46, v36
	v_cvt_pk_bf16_f32 v44, v56, v57
	s_nop 0
	v_addc_co_u32_e32 v47, vcc, 0, v37, vcc
	v_add_co_u32_e32 v36, vcc, 0xec18000, v36
	v_cvt_pk_bf16_f32 v45, v58, v59
	v_cvt_pk_bf16_f32 v40, v40, v41
	v_cvt_pk_bf16_f32 v41, v42, v43
	v_addc_co_u32_e32 v37, vcc, 0, v37, vcc
	global_store_dwordx2 v[46:47], v[44:45], off
	global_store_dwordx2 v[36:37], v[40:41], off
	s_waitcnt vmcnt(4) lgkmcnt(0)
	s_branch .LBB0_710
